# FFN conv epilogue: two rows per iteration, interleaved chains, no per-row branch or 64-bit mad
# speedup vs baseline: 1.0776x; 1.0147x over previous
; DI u16 f2bf(float a) { return (u16)(pack2(a, 0.f) & 0xffffu); }
; DI float sigmoidf_(float x) { return __builtin_amdgcn_rcpf(1.f + __builtin_amdgcn_exp2f(-1.44269504089f * x)); }
;   DI void finish(int tm, int tn, char* smem, int pass, int wave_s) const {
;     ...
;     const int ng = (tn * 2 + pass) * 64, nv = 2816 + ng;
;     const float g0 = (cw + ng)[c], g1 = (cw + 5632 + ng)[c], g2 = (cw + 2 * 5632 + ng)[c], gb = (cb + ng)[c];
;     const float v0 = (cw + nv)[c], v1 = (cw + 5632 + nv)[c], v2 = (cw + 2 * 5632 + nv)[c], vb = (cb + nv)[c];
;     u16* dst = ACT + ((size_t)b * SEQ + j * 254) * 2816 + ng;
;     const int rr0 = 2 + 32 * wv;
;     float ug2 = U[(rr0 - 2) * 129 + c], ug1 = U[(rr0 - 1) * 129 + c];
;     float uv2 = U[(rr0 - 2) * 129 + 64 + c], uv1 = U[(rr0 - 1) * 129 + 64 + c];
;     const int nrow = min(32, 256 - rr0);
;     for (int q = 0; q < nrow; ++q) {
;       const int rr = rr0 + q;
;       const float ug0 = U[rr * 129 + c], uv0 = U[rr * 129 + 64 + c];
;       const float gate = gb + g0 * ug2 + g1 * ug1 + g2 * ug0;
;       const float val = vb + v0 * uv2 + v1 * uv1 + v2 * uv0;
;       const int sq = j * 254 + rr - 2;
;       if (sq < SEQ) (dst + (size_t)(rr - 2) * 2816)[c] = f2bf(gate * sigmoidf_(gate) * val);
;       ug2 = ug1; ug1 = ug0; uv2 = uv1; uv1 = uv0;
;     }
.LBB0_3604:
	s_mul_i32 s4, s22, 0xffffffdf
	s_add_i32 s7, s4, s74
	s_mulk_i32 s7, 0xfe
	s_lshl_b32 s6, s24, 7
	s_lshl_b64 s[4:5], s[22:23], 13
	s_ashr_i32 s8, s7, 31
	s_add_u32 s4, s4, s7
	s_addc_u32 s5, s5, s8
	s_mulk_i32 s5, 0x1600
	s_mul_hi_u32 s7, s4, 0x1600
	s_add_i32 s7, s7, s5
	s_mulk_i32 s4, 0x1600
	s_add_u32 s4, s84, s4
	s_addc_u32 s23, s85, s7
	s_ashr_i32 s7, s6, 31
	s_lshl_b64 s[8:9], s[6:7], 1
	v_readlane_b32 s5, v254, 0
	s_add_u32 s8, s4, s8
	s_waitcnt lgkmcnt(0)
	s_barrier
	s_addc_u32 s9, s23, s9
	s_lshl_b32 s4, s5, 5
	s_or_b32 s23, s4, 2
	v_mov_b32_e32 v158, v171
	s_cmpk_lt_i32 s23, 0x100
	s_mulk_i32 s66, 0x7f0
	s_mulk_i32 s68, 0xfe
	s_mulk_i32 s69, 0xfe
	s_mulk_i32 s22, 0x20be
	s_cbranch_scc0 .LBB0_3609
	s_lshl_b64 s[24:25], s[6:7], 2
	s_add_u32 s74, s24, 0x2c00
	s_addc_u32 s75, s25, 0
	v_ashrrev_i32_e32 v159, 31, v158
	s_add_u32 s26, s35, s74
	s_addc_u32 s27, s36, s75
	v_lshlrev_b64 v[160:161], 2, v[158:159]
	v_lshl_add_u64 v[150:151], s[26:27], 0, v[160:161]
	s_add_u32 s26, s16, s74
	s_addc_u32 s27, s17, s75
	v_lshl_add_u64 v[152:153], s[26:27], 0, v[160:161]
	s_add_u32 s26, s14, s74
	s_addc_u32 s27, s15, s75
	v_lshl_add_u64 v[154:155], s[26:27], 0, v[160:161]
	s_add_u32 s26, s31, s74
	s_addc_u32 s27, s34, s75
	v_lshl_add_u64 v[156:157], s[26:27], 0, v[160:161]
	s_add_u32 s26, s35, s24
	s_addc_u32 s27, s36, s25
	v_lshl_add_u64 v[162:163], s[26:27], 0, v[160:161]
	s_add_u32 s26, s16, s24
	s_addc_u32 s27, s17, s25
	flat_load_dword v150, v[150:151]
	s_mulk_i32 s5, 0x4080
	flat_load_dword v151, v[162:163]
	v_lshl_add_u64 v[162:163], s[26:27], 0, v[160:161]
	s_add_u32 s26, s14, s24
	s_addc_u32 s27, s15, s25
	s_add_u32 s24, s31, s24
	s_addc_u32 s25, s34, s25
	flat_load_dword v152, v[152:153]
	v_lshl_add_u64 v[148:149], v[158:159], 1, s[8:9]
	flat_load_dword v154, v[154:155]
	s_sub_i32 s23, 0x100, s23
	flat_load_dword v156, v[156:157]
	s_nop 0
	flat_load_dword v153, v[162:163]
	v_lshl_add_u64 v[162:163], s[26:27], 0, v[160:161]
	v_lshl_add_u64 v[160:161], s[24:25], 0, v[160:161]
	flat_load_dword v155, v[162:163]
	flat_load_dword v157, v[160:161]
	v_lshlrev_b32_e32 v162, 2, v158
	s_add_i32 s24, s5, 0
	v_add_u32_e32 v160, s24, v162
	ds_read2_b32 v[158:159], v160 offset0:129 offset1:193
	ds_read2st64_b32 v[160:161], v160 offset1:1
	s_min_u32 s5, s23, 32
	s_add_i32 s23, s66, s68
	s_sub_i32 s23, s23, s69
	s_sub_i32 s23, s23, s22
	s_addk_i32 s24, 0x408
	s_add_i32 s23, s23, 2
	v_add_u32_e32 v210, s24, v162
	s_waitcnt lgkmcnt(0)
	v_mov_b32_e32 v162, v161
	v_mov_b32_e32 v163, v160
	s_waitcnt vmcnt(0)
	s_sub_i32 s26, 0x2002, s23
	s_sub_i32 s26, s26, s4
	s_max_i32 s26, s26, 0
	s_min_i32 s26, s26, s5
	s_lshr_b32 s26, s26, 1
	s_cmp_eq_u32 s26, 0
	s_cbranch_scc1 .LBB0_3609
	v_add_u32_e32 v158, 0xfffffbf8, v210
	ds_read2_b32 v[212:213], v158 offset0:64
	ds_read2_b32 v[214:215], v158 offset0:193 offset1:129
	ds_read2_b32 v[216:217], v210 offset0:64
	ds_read2_b32 v[218:219], v210 offset0:193 offset1:129
	v_mad_i64_i32 v[228:229], s[24:25], s4, v247, v[148:149]
	v_mov_b32_e32 v162, 0x2c00
	v_mov_b32_e32 v163, 0
	v_mov_b32_e32 v160, 0x1600
	v_mov_b32_e32 v161, 0
	v_lshl_add_u64 v[230:231], v[228:229], 0, v[160:161]
.Lcv0_loop:
	s_waitcnt lgkmcnt(0)
	v_pk_fma_f32 v[220:221], v[156:157], v[212:213], v[150:151]
	v_pk_fma_f32 v[222:223], v[156:157], v[214:215], v[150:151]
	v_pk_fma_f32 v[220:221], v[154:155], v[214:215], v[220:221]
	v_pk_fma_f32 v[222:223], v[154:155], v[216:217], v[222:223]
	v_pk_fma_f32 v[220:221], v[152:153], v[216:217], v[220:221]
	v_pk_fma_f32 v[222:223], v[152:153], v[218:219], v[222:223]
	v_mov_b64_e32 v[212:213], v[216:217]
	v_mov_b64_e32 v[214:215], v[218:219]
	v_add_u32_e32 v210, 0x408, v210
	ds_read2_b32 v[216:217], v210 offset0:64
	ds_read2_b32 v[218:219], v210 offset0:193 offset1:129
	v_mul_f32_e32 v224, 0xbfb8aa3b, v221
	v_mul_f32_e32 v225, 0xbfb8aa3b, v223
	v_exp_f32_e32 v224, v224
	v_exp_f32_e32 v225, v225
	v_add_f32_e32 v224, 1.0, v224
	v_add_f32_e32 v225, 1.0, v225
	v_rcp_f32_e32 v224, v224
	v_rcp_f32_e32 v225, v225
	v_mul_f32_e32 v224, v221, v224
	v_mul_f32_e32 v225, v223, v225
	v_mul_f32_e32 v224, v220, v224
	v_mul_f32_e32 v225, v222, v225
	v_cvt_pk_bf16_f32 v226, v224, v224
	v_cvt_pk_bf16_f32 v227, v225, v225
	global_store_short v[228:229], v226, off
	global_store_short v[230:231], v227, off
	v_lshl_add_u64 v[228:229], v[228:229], 0, v[162:163]
	v_lshl_add_u64 v[230:231], v[230:231], 0, v[162:163]
	s_add_i32 s26, s26, -1
	s_cmp_lg_u32 s26, 0
	s_cbranch_scc1 .Lcv0_loop
	s_branch .LBB0_3609

; DI int mk_wv(int w) { asm volatile("" : "+s"(w)); return w; }
; DI int mk_lane() { int l = __builtin_amdgcn_mbcnt_hi(~0u, __builtin_amdgcn_mbcnt_lo(~0u, 0u)); asm volatile("" : "+v"(l)); return l; }
; DI u16 f2bf(float a) { return (u16)(pack2(a, 0.f) & 0xffffu); }
; DI float sigmoidf_(float x) { return __builtin_amdgcn_rcpf(1.f + __builtin_amdgcn_exp2f(-1.44269504089f * x)); }
;   DI void finish(int tm, int tn, char* smem, int pass, int wave_s) const {
;     __syncthreads();
;     const float* U = (const float*)smem;
;     const int b = tm / 33, j = tm - b * 33;
;     const int wv = mk_wv(wave_s), c = mk_lane();
;     const int ng = (tn * 2 + pass) * 64, nv = 2816 + ng;
;     const float g0 = (cw + ng)[c], g1 = (cw + 5632 + ng)[c], g2 = (cw + 2 * 5632 + ng)[c], gb = (cb + ng)[c];
;     const float v0 = (cw + nv)[c], v1 = (cw + 5632 + nv)[c], v2 = (cw + 2 * 5632 + nv)[c], vb = (cb + nv)[c];
;     u16* dst = ACT + ((size_t)b * SEQ + j * 254) * 2816 + ng;
;     const int rr0 = 2 + 32 * wv;
;     float ug2 = U[(rr0 - 2) * 129 + c], ug1 = U[(rr0 - 1) * 129 + c];
;     float uv2 = U[(rr0 - 2) * 129 + 64 + c], uv1 = U[(rr0 - 1) * 129 + 64 + c];
;     const int nrow = min(32, 256 - rr0);
;     for (int q = 0; q < nrow; ++q) {
;       const int rr = rr0 + q;
;       const float ug0 = U[rr * 129 + c], uv0 = U[rr * 129 + 64 + c];
;       const float gate = gb + g0 * ug2 + g1 * ug1 + g2 * ug0;
;       const float val = vb + v0 * uv2 + v1 * uv1 + v2 * uv0;
;       const int sq = j * 254 + rr - 2;
;       if (sq < SEQ) (dst + (size_t)(rr - 2) * 2816)[c] = f2bf(gate * sigmoidf_(gate) * val);
;       ug2 = ug1; ug1 = ug0; uv2 = uv1; uv1 = uv0;
;     }
;     __syncthreads();
;   }
.LBB0_3625:
	v_readlane_b32 s5, v254, 0
	s_waitcnt lgkmcnt(0)
	s_barrier
	s_lshl_b32 s4, s5, 5
	s_or_b32 s23, s4, 2
	v_mov_b32_e32 v12, v171
	s_cmpk_gt_i32 s23, 0xff
	s_cbranch_scc1 .LBB0_3585
	s_or_b32 s24, s6, 64
	v_ashrrev_i32_e32 v13, 31, v12
	s_ashr_i32 s25, s24, 31
	v_lshl_add_u64 v[2:3], v[12:13], 1, s[8:9]
	s_lshl_b64 s[8:9], s[6:7], 2
	s_add_u32 s26, s8, 0x2d00
	s_addc_u32 s27, s9, 0
	s_add_u32 s8, s35, s26
	s_addc_u32 s9, s36, s27
	v_lshlrev_b64 v[14:15], 2, v[12:13]
	v_lshl_add_u64 v[4:5], s[8:9], 0, v[14:15]
	s_add_u32 s8, s16, s26
	s_addc_u32 s9, s17, s27
	v_lshl_add_u64 v[6:7], s[8:9], 0, v[14:15]
	s_add_u32 s8, s14, s26
	s_addc_u32 s9, s15, s27
	v_lshl_add_u64 v[8:9], s[8:9], 0, v[14:15]
	s_add_u32 s8, s31, s26
	s_addc_u32 s9, s34, s27
	s_lshl_b64 s[6:7], s[6:7], 2
	v_lshl_add_u64 v[10:11], s[8:9], 0, v[14:15]
	s_add_u32 s8, s35, s6
	s_addc_u32 s9, s36, s7
	v_lshl_add_u64 v[16:17], s[8:9], 0, v[14:15]
	flat_load_dword v4, v[4:5]
	s_lshl_b64 s[8:9], s[24:25], 2
	flat_load_dword v5, v[16:17] offset:256
	v_lshl_add_u64 v[16:17], s[16:17], 0, v[14:15]
	v_lshl_add_u64 v[16:17], v[16:17], 0, s[8:9]
	s_add_u32 s6, s31, s6
	flat_load_dword v6, v[6:7]
	s_addc_u32 s7, s34, s7
	flat_load_dword v8, v[8:9]
	s_mulk_i32 s5, 0x4080
	flat_load_dword v10, v[10:11]
	v_lshlrev_b32_e32 v0, 2, v12
	flat_load_dword v7, v[16:17]
	v_lshl_add_u64 v[16:17], s[14:15], 0, v[14:15]
	v_lshl_add_u64 v[16:17], v[16:17], 0, s[8:9]
	v_lshl_add_u64 v[14:15], s[6:7], 0, v[14:15]
	flat_load_dword v9, v[16:17]
	flat_load_dword v11, v[14:15] offset:256
	s_add_i32 s7, s5, 0
	v_add_u32_e32 v14, s7, v0
	ds_read2_b32 v[12:13], v14 offset0:129 offset1:193
	ds_read2st64_b32 v[14:15], v14 offset1:1
	s_sub_i32 s6, 0x100, s23
	s_add_i32 s66, s66, s68
	s_min_u32 s5, s6, 32
	s_sub_i32 s6, s66, s69
	s_sub_i32 s6, s6, s22
	s_addk_i32 s7, 0x408
	s_add_i32 s6, s6, 2
	v_add_u32_e32 v0, s7, v0
	s_waitcnt lgkmcnt(0)
	v_mov_b32_e32 v16, v15
	v_mov_b32_e32 v17, v14
	s_waitcnt vmcnt(0)
	s_sub_i32 s26, 0x2002, s6
	s_sub_i32 s26, s26, s4
	s_max_i32 s26, s26, 0
	s_min_i32 s26, s26, s5
	s_lshr_b32 s26, s26, 1
	s_cmp_eq_u32 s26, 0
	s_cbranch_scc1 .LBB0_3585
	v_add_u32_e32 v158, 0xfffffbf8, v0
	ds_read2_b32 v[212:213], v158 offset0:64
	ds_read2_b32 v[214:215], v158 offset0:193 offset1:129
	ds_read2_b32 v[216:217], v0 offset0:64
	ds_read2_b32 v[218:219], v0 offset0:193 offset1:129
	v_mad_i64_i32 v[228:229], s[8:9], s4, v247, v[2:3]
	v_mov_b32_e32 v162, 0x2c00
	v_mov_b32_e32 v163, 0
	v_mov_b32_e32 v160, 0x1600
	v_mov_b32_e32 v161, 0
	v_lshl_add_u64 v[230:231], v[228:229], 0, v[160:161]
.Lcv1_loop:
	s_waitcnt lgkmcnt(0)
	v_pk_fma_f32 v[220:221], v[10:11], v[212:213], v[4:5]
	v_pk_fma_f32 v[222:223], v[10:11], v[214:215], v[4:5]
	v_pk_fma_f32 v[220:221], v[8:9], v[214:215], v[220:221]
	v_pk_fma_f32 v[222:223], v[8:9], v[216:217], v[222:223]
	v_pk_fma_f32 v[220:221], v[6:7], v[216:217], v[220:221]
	v_pk_fma_f32 v[222:223], v[6:7], v[218:219], v[222:223]
	v_mov_b64_e32 v[212:213], v[216:217]
	v_mov_b64_e32 v[214:215], v[218:219]
	v_add_u32_e32 v0, 0x408, v0
	ds_read2_b32 v[216:217], v0 offset0:64
	ds_read2_b32 v[218:219], v0 offset0:193 offset1:129
	v_mul_f32_e32 v224, 0xbfb8aa3b, v221
	v_mul_f32_e32 v225, 0xbfb8aa3b, v223
	v_exp_f32_e32 v224, v224
	v_exp_f32_e32 v225, v225
	v_add_f32_e32 v224, 1.0, v224
	v_add_f32_e32 v225, 1.0, v225
	v_rcp_f32_e32 v224, v224
	v_rcp_f32_e32 v225, v225
	v_mul_f32_e32 v224, v221, v224
	v_mul_f32_e32 v225, v223, v225
	v_mul_f32_e32 v224, v220, v224
	v_mul_f32_e32 v225, v222, v225
	v_cvt_pk_bf16_f32 v226, v224, v224
	v_cvt_pk_bf16_f32 v227, v225, v225
	global_store_short v[228:229], v226, off offset:128
	global_store_short v[230:231], v227, off offset:128
	v_lshl_add_u64 v[228:229], v[228:229], 0, v[162:163]
	v_lshl_add_u64 v[230:231], v[230:231], 0, v[162:163]
	s_add_i32 s26, s26, -1
	s_cmp_lg_u32 s26, 0
	s_cbranch_scc1 .Lcv1_loop
	s_branch .LBB0_3585
